# seam streaming: iterations beyond the 12 staged loads issue a one-dword dummy load instead of a duplicate 1 KB stage load
# baseline (speedup 1.0000x reference)
.LBB0_898:
	s_add_i32 s9, s3, -1
	s_min_u32 s9, s9, s2
	s_lshl_b32 s9, s9, 6
	s_waitcnt vmcnt(1)
	ds_write_b128 v142, v[112:115] offset:16384
	s_waitcnt vmcnt(0)
	ds_write_b128 v142, v[116:119] offset:24576
	v_mad_u64_u32 v[64:65], s[18:19], s9, v237, v[132:133]
	global_load_dwordx4 v[120:123], v[64:65], off offset:2048
	global_load_dwordx4 v[124:127], v[136:137], off offset:-128
	ds_read_b128 v[64:67], v144 offset:8192
	ds_read_b128 v[68:71], v144 offset:12288
	ds_read_b128 v[72:75], v141 offset:8192
	ds_read_b128 v[76:79], v141 offset:12288
	v_exp_f32_e32 v151, v48
	v_exp_f32_e32 v152, v49
	s_waitcnt lgkmcnt(3)
	v_mfma_f32_32x32x16_bf16 v[16:31], v[64:67], v[80:83], v[16:31]
	v_exp_f32_e32 v153, v50
	v_exp_f32_e32 v154, v51
	ds_read_b128 v[48:51], v140 offset:8192
	ds_read_b128 v[64:67], v140 offset:12288
	v_exp_f32_e32 v155, v52
	s_waitcnt lgkmcnt(4)
	v_mfma_f32_32x32x16_bf16 v[0:15], v[68:71], v[80:83], v[0:15]
	v_exp_f32_e32 v156, v53
	v_exp_f32_e32 v159, v54
	v_exp_f32_e32 v160, v55
	v_exp_f32_e32 v162, v57
	s_waitcnt lgkmcnt(3)
	v_mfma_f32_32x32x16_bf16 v[16:31], v[72:75], v[84:87], v[16:31]
	ds_read_b128 v[68:71], v139 offset:8192
	ds_read_b128 v[80:83], v139 offset:12288
	v_add_f32_e32 v157, v155, v151
	v_add_f32_e32 v158, v156, v152
	ds_read_b128 v[52:55], v164
	ds_read_b128 v[72:75], v164 offset:4096
	v_add_f32_e32 v161, v159, v153
	s_waitcnt lgkmcnt(6)
	v_mfma_f32_32x32x16_bf16 v[0:15], v[76:79], v[84:87], v[0:15]
	v_exp_f32_e32 v77, v56
	v_add_f32_e32 v76, v160, v154
	v_exp_f32_e32 v62, v62
	ds_read_b128 v[112:115], v165
	ds_read_b128 v[116:119], v165 offset:4096
	v_cvt_pk_bf16_f32 v56, v151, v152
	s_waitcnt lgkmcnt(7)
	v_mfma_f32_32x32x16_bf16 v[16:31], v[48:51], v[88:91], v[16:31]
	v_exp_f32_e32 v49, v58
	v_exp_f32_e32 v50, v59
	v_add_f32_e32 v48, v77, v157
	v_add_f32_e32 v51, v162, v158
	v_add_f32_e32 v78, v49, v161
	v_add_f32_e32 v76, v50, v76
	s_waitcnt lgkmcnt(6)
	v_mfma_f32_32x32x16_bf16 v[0:15], v[64:67], v[88:91], v[0:15]
	v_exp_f32_e32 v60, v60
	v_add_f32_e32 v151, v62, v78
	v_exp_f32_e32 v61, v61
	v_exp_f32_e32 v63, v63
	v_cvt_pk_bf16_f32 v59, v159, v160
	v_exp_f32_e32 v160, v33
	s_waitcnt lgkmcnt(5)
	v_mfma_f32_32x32x16_bf16 v[16:31], v[68:71], v[92:95], v[16:31]
	v_cvt_pk_bf16_f32 v57, v153, v154
	v_cvt_pk_bf16_f32 v58, v155, v156
	v_add_f32_e32 v48, v60, v48
	v_add_f32_e32 v51, v61, v51
	v_cvt_pk_bf16_f32 v49, v49, v50
	s_waitcnt lgkmcnt(4)
	v_mfma_f32_32x32x16_bf16 v[0:15], v[80:83], v[92:95], v[0:15]
	s_sub_u32 vcc_lo, s3, 5
	s_lshr_b32 vcc_lo, vcc_lo, 1
	s_and_b32 vcc_lo, vcc_lo, 15
	v_readfirstlane_b32 s18, v171
	s_cmp_lt_u32 vcc_lo, 12
	s_cbranch_scc1 .Lst_real
	global_load_dword v174, v177, s[12:13]
	s_branch .Lst_done
.Lst_real:
	s_cmp_lt_u32 vcc_lo, 6
	s_cbranch_scc0 .Lst_6
	s_cmp_lt_u32 vcc_lo, 3
	s_cbranch_scc0 .Lst_3
	s_cmp_lt_u32 vcc_lo, 1
	s_cbranch_scc0 .Lst_1
	s_add_u32 m0, s18, 0x7600
	s_nop 0
	global_load_lds_dwordx4 v168, s[12:13] offset:2560
	s_branch .Lst_done
.Lst_1:
	s_cmp_lt_u32 vcc_lo, 2
	s_cbranch_scc0 .Lst_2
	s_add_u32 m0, s18, 0x95e0
	s_nop 0
	global_load_lds_dwordx4 v168, s[12:13] offset:2592
	s_branch .Lst_done
.Lst_2:
	s_add_u32 m0, s18, 0xb5c0
	s_nop 0
	global_load_lds_dwordx4 v168, s[12:13] offset:2624
	s_branch .Lst_done
.Lst_3:
	s_cmp_lt_u32 vcc_lo, 4
	s_cbranch_scc0 .Lst_4
	s_add_u32 m0, s18, 0xd5a0
	s_nop 0
	global_load_lds_dwordx4 v168, s[12:13] offset:2656
	s_branch .Lst_done
.Lst_4:
	s_cmp_lt_u32 vcc_lo, 5
	s_cbranch_scc0 .Lst_5
	s_add_u32 m0, s18, 0xfc00
	s_nop 0
	global_load_lds_dwordx4 v168, s[14:15] offset:1024
	s_branch .Lst_done

.Lst_6:
	s_cmp_lt_u32 vcc_lo, 9
	s_cbranch_scc0 .Lst_9
	s_cmp_lt_u32 vcc_lo, 7
	s_cbranch_scc0 .Lst_7
	s_add_u32 m0, s18, 0x13bc0
	s_nop 0
	global_load_lds_dwordx4 v168, s[14:15] offset:1088
	s_branch .Lst_done
.Lst_7:
	s_cmp_lt_u32 vcc_lo, 8
	s_cbranch_scc0 .Lst_8
	s_add_u32 m0, s18, 0x15ba0
	s_nop 0
	global_load_lds_dwordx4 v168, s[14:15] offset:1120
	s_branch .Lst_done
.Lst_8:
	s_mov_b64 vcc, s[34:35]
	s_add_u32 m0, s18, 0x17800
	s_nop 0
	global_load_lds_dwordx4 v170, vcc offset:2048
	s_branch .Lst_done
.Lst_9:
	s_cmp_lt_u32 vcc_lo, 10
	s_cbranch_scc0 .Lst_10
	s_add_u32 vcc_lo, s34, 0x48000
	s_addc_u32 vcc_hi, s35, 0
	s_add_u32 m0, s18, 0x19800
	s_nop 0
	global_load_lds_dwordx4 v170, vcc offset:2048
	s_branch .Lst_done

.Lst_11:
	s_add_u32 m0, s18, 0x1e000
	s_nop 0
	global_load_lds_dwordx4 v169, s[10:11]
	s_branch .Lst_done
.Lst_done:
	v_exp_f32_e32 v95, v32
	v_add_f32_e32 v32, v63, v76
	v_add_f32_e32 v163, v160, v51
	v_add_f32_e32 v161, v95, v48
	v_cvt_pk_bf16_f32 v48, v77, v162
	v_cvt_pk_bf16_f32 v51, v62, v63
	s_waitcnt lgkmcnt(3)
	v_mfma_f32_32x32x16_bf16 v[78:93], v[52:55], v[96:99], 0
	v_cvt_pk_bf16_f32 v50, v60, v61
	v_exp_f32_e32 v60, v34
	v_exp_f32_e32 v61, v35
	v_exp_f32_e32 v36, v36
	v_exp_f32_e32 v37, v37
	v_exp_f32_e32 v38, v38
	v_exp_f32_e32 v39, v39
	s_waitcnt lgkmcnt(2)
	v_mfma_f32_32x32x16_bf16 v[62:77], v[72:75], v[96:99], 0
	ds_read_b128 v[52:55], v166
	ds_read_b128 v[152:155], v166 offset:4096
	v_add_f32_e32 v151, v60, v151
	v_add_f32_e32 v162, v61, v32
	s_waitcnt lgkmcnt(3)
	v_mfma_f32_32x32x16_bf16 v[78:93], v[112:115], v[100:103], v[78:93]
	v_add_f32_e32 v112, v36, v161
	v_add_f32_e32 v113, v37, v163
	v_add_f32_e32 v114, v38, v151
	v_exp_f32_e32 v115, v40
	v_add_f32_e32 v40, v39, v162
	ds_read_b128 v[32:35], v167
	ds_read_b128 v[156:159], v167 offset:4096
	s_waitcnt lgkmcnt(4)
	v_mfma_f32_32x32x16_bf16 v[62:77], v[116:119], v[100:103], v[62:77]
	v_exp_f32_e32 v116, v41
	v_add_f32_e32 v41, v115, v112
	s_min_u32 s9, s3, s2
	s_lshl_b32 s9, s9, 6
	v_add_f32_e32 v112, v116, v113
	s_waitcnt lgkmcnt(3)
	v_mfma_f32_32x32x16_bf16 v[78:93], v[52:55], v[104:107], v[78:93]
	v_cvt_pk_bf16_f32 v54, v36, v37
	v_exp_f32_e32 v37, v42
	v_cvt_pk_bf16_f32 v55, v38, v39
	v_exp_f32_e32 v38, v43
	v_exp_f32_e32 v39, v44
	v_exp_f32_e32 v44, v45
	v_exp_f32_e32 v45, v46
	v_exp_f32_e32 v46, v47
	v_cvt_pk_bf16_f32 v52, v95, v160
	v_cvt_pk_bf16_f32 v53, v60, v61
	v_add_f32_e32 v36, v37, v114
	v_add_f32_e32 v43, v38, v40
	v_add_f32_e32 v40, v39, v41
	v_add_f32_e32 v42, v44, v112
	v_add_f32_e32 v41, v45, v36
	v_add_f32_e32 v43, v46, v43
	v_cvt_pk_bf16_f32 v36, v115, v116
	v_cvt_pk_bf16_f32 v37, v37, v38
	v_cvt_pk_bf16_f32 v38, v39, v44
	v_cvt_pk_bf16_f32 v39, v45, v46
	s_waitcnt lgkmcnt(1)
	v_mfma_f32_32x32x16_bf16 v[78:93], v[32:35], v[108:111], v[78:93]
	s_waitcnt lgkmcnt(0)
	s_barrier
	v_mad_u64_u32 v[32:33], s[18:19], s9, v237, v[132:133]
	global_load_dwordx4 v[112:115], v[32:33], off offset:2048
	global_load_dwordx4 v[116:119], v[136:137], off
	v_add_f32_e64 v32, v40, v42
	v_add_f32_e64 v33, v41, v43
	s_waitcnt vmcnt(4)
	ds_write_b128 v142, v[120:123]
	s_waitcnt vmcnt(3)
	ds_write_b128 v142, v[124:127] offset:8192
	v_mfma_f32_32x32x16_bf16 v[62:77], v[152:155], v[104:107], v[62:77]
	v_add_f32_e32 v32, v32, v33
	v_add_f32_e32 v150, v150, v32
	s_waitcnt lgkmcnt(2)
	v_mfma_f32_32x32x16_bf16 v[62:77], v[156:159], v[108:111], v[62:77]
	ds_read_b128 v[32:35], v144 offset:24576
	ds_read_b128 v[40:43], v144 offset:28672
	ds_read_b128 v[44:47], v141 offset:24576
	ds_read_b128 v[120:123], v141 offset:28672
	v_exp_f32_e32 v60, v78
	s_waitcnt lgkmcnt(3)
	v_mfma_f32_32x32x16_bf16 v[16:31], v[32:35], v[56:59], v[16:31]
	v_exp_f32_e32 v61, v79
	v_exp_f32_e32 v95, v80
	v_exp_f32_e32 v81, v81
	ds_read_b128 v[152:155], v140 offset:24576
	ds_read_b128 v[156:159], v140 offset:28672
	s_waitcnt lgkmcnt(4)
	v_mfma_f32_32x32x16_bf16 v[0:15], v[40:43], v[56:59], v[0:15]
	v_exp_f32_e32 v82, v82
	v_exp_f32_e32 v83, v83
	v_add_f32_e32 v78, v82, v60
	v_add_f32_e32 v79, v83, v61
	s_waitcnt lgkmcnt(2)
	v_mfma_f32_32x32x16_bf16 v[0:15], v[120:123], v[48:51], v[0:15]
	ds_read_b128 v[56:59], v139 offset:24576
	ds_read_b128 v[160:163], v139 offset:28672
	ds_read_b128 v[40:43], v164 offset:16384
	ds_read_b128 v[32:35], v164 offset:20480
	v_cvt_pk_bf16_f32 v82, v82, v83
	v_exp_f32_e32 v151, v62
	v_exp_f32_e32 v64, v64
	v_exp_f32_e32 v65, v65
	v_mfma_f32_32x32x16_bf16 v[16:31], v[44:47], v[48:51], v[16:31]
	v_exp_f32_e32 v44, v84
	v_exp_f32_e32 v45, v85
	v_exp_f32_e32 v84, v86
	v_exp_f32_e32 v85, v87
	v_add_f32_e32 v46, v44, v95
	v_add_f32_e32 v47, v45, v81
	v_add_f32_e32 v48, v84, v78
	s_waitcnt lgkmcnt(4)
	v_mfma_f32_32x32x16_bf16 v[0:15], v[156:159], v[52:55], v[0:15]
	v_add_f32_e32 v49, v85, v79
	v_exp_f32_e32 v78, v88
	v_exp_f32_e32 v79, v89
	v_exp_f32_e32 v87, v92
	v_cvt_pk_bf16_f32 v83, v44, v45
	v_exp_f32_e32 v44, v90
	v_mfma_f32_32x32x16_bf16 v[16:31], v[152:155], v[52:55], v[16:31]
	v_exp_f32_e32 v45, v91
	v_exp_f32_e32 v92, v93
	v_add_f32_e32 v46, v78, v46
	v_add_f32_e32 v47, v79, v47
	ds_read_b128 v[124:127], v165 offset:16384
	ds_read_b128 v[120:123], v165 offset:20480
	s_waitcnt lgkmcnt(4)
	v_mfma_f32_32x32x16_bf16 v[0:15], v[160:163], v[36:39], v[0:15]
	v_exp_f32_e32 v160, v63
	v_cvt_pk_bf16_f32 v80, v60, v61
	v_cvt_pk_bf16_f32 v81, v95, v81
	v_add_f32_e32 v48, v44, v48
	v_add_f32_e32 v49, v45, v49
	v_add_f32_e32 v46, v87, v46
	v_add_f32_e32 v47, v92, v47
	v_mfma_f32_32x32x16_bf16 v[16:31], v[56:59], v[36:39], v[16:31]
	v_add_f32_e32 v161, v151, v48
	v_add_f32_e32 v162, v160, v49
	v_cvt_pk_bf16_f32 v84, v84, v85
	v_cvt_pk_bf16_f32 v85, v78, v79
	v_cvt_pk_bf16_f32 v86, v44, v45
	v_add_f32_e32 v78, v64, v46
	v_add_f32_e32 v79, v65, v47
	s_waitcnt lgkmcnt(3)
	v_mfma_f32_32x32x16_bf16 v[48:63], v[40:43], v[96:99], 0
	ds_read_b128 v[88:91], v166 offset:16384
	ds_read_b128 v[152:155], v166 offset:20480
	v_exp_f32_e32 v66, v66
	v_exp_f32_e32 v67, v67
	v_exp_f32_e32 v68, v68
	v_exp_f32_e32 v69, v69
	v_cvt_pk_bf16_f32 v87, v87, v92
	s_waitcnt lgkmcnt(4)
	v_mfma_f32_32x32x16_bf16 v[32:47], v[32:35], v[96:99], 0
	ds_read_b128 v[156:159], v167 offset:16384
	ds_read_b128 v[92:95], v167 offset:20480
	v_add_f32_e32 v161, v66, v161
	v_add_f32_e32 v162, v67, v162
	v_add_f32_e32 v78, v68, v78
	v_add_f32_e32 v79, v69, v79
	s_waitcnt lgkmcnt(5)
	v_mfma_f32_32x32x16_bf16 v[48:63], v[124:127], v[100:103], v[48:63]
	v_exp_f32_e32 v70, v70
	v_exp_f32_e32 v71, v71
	s_add_i32 s9, s3, 2
	s_add_i32 s3, s3, -2
	v_lshl_add_u64 v[136:137], v[136:137], 0, s[22:23]
	s_waitcnt lgkmcnt(4)
	v_mfma_f32_32x32x16_bf16 v[32:47], v[120:123], v[100:103], v[32:47]
	v_add_f32_e32 v120, v70, v161
	v_add_f32_e32 v121, v71, v162
	s_cmp_lt_u32 s3, s2
	s_mov_b32 s3, s9
	s_waitcnt lgkmcnt(3)
	v_mfma_f32_32x32x16_bf16 v[48:63], v[88:91], v[104:107], v[48:63]
	v_cvt_pk_bf16_f32 v91, v68, v69
	v_exp_f32_e32 v68, v72
	v_exp_f32_e32 v69, v73
	v_exp_f32_e32 v72, v74
	v_exp_f32_e32 v73, v75
	v_exp_f32_e32 v74, v76
	v_exp_f32_e32 v75, v77
	s_waitcnt lgkmcnt(2)
	v_mfma_f32_32x32x16_bf16 v[32:47], v[152:155], v[104:107], v[32:47]
	v_cvt_pk_bf16_f32 v88, v151, v160
	v_cvt_pk_bf16_f32 v89, v64, v65
	v_cvt_pk_bf16_f32 v90, v66, v67
	v_add_f32_e32 v65, v68, v78
	v_add_f32_e32 v67, v69, v79
	s_waitcnt lgkmcnt(1)
	v_mfma_f32_32x32x16_bf16 v[48:63], v[156:159], v[108:111], v[48:63]
	v_add_f32_e32 v64, v72, v120
	v_add_f32_e32 v66, v73, v121
	v_add_f32_e32 v65, v74, v65
	v_add_f32_e32 v67, v75, v67
	s_waitcnt lgkmcnt(0)
	v_mfma_f32_32x32x16_bf16 v[32:47], v[92:95], v[108:111], v[32:47]
	v_cvt_pk_bf16_f32 v92, v70, v71
	v_cvt_pk_bf16_f32 v93, v68, v69
	v_cvt_pk_bf16_f32 v94, v72, v73
	v_cvt_pk_bf16_f32 v95, v74, v75
	v_add_f32_e64 v64, v64, v66
	v_add_f32_e64 v65, v65, v67
	s_waitcnt lgkmcnt(0)
	s_barrier
	v_add_f32_e32 v64, v64, v65
	v_add_f32_e32 v150, v150, v64
	s_cbranch_scc1 .LBB0_898
	v_ashrrev_i32_e32 v64, 1, v129
	v_and_or_b32 v132, v64, s88, v148
	v_lshlrev_b32_e32 v176, 4, v138
	s_waitcnt vmcnt(1)
	ds_write_b128 v142, v[112:115] offset:16384
	s_waitcnt vmcnt(0)
	ds_write_b128 v142, v[116:119] offset:24576
	ds_read_b128 v[124:127], v172 offset:32768
	ds_read_b128 v[120:123], v172 offset:40960
	ds_read_b128 v[116:119], v172 offset:49152
	ds_read_b128 v[112:115], v172 offset:57344
	v_ashrrev_i32_e32 v133, 31, v132
	ds_read_b128 v[128:131], v144 offset:8192
	ds_read_b128 v[134:137], v144 offset:12288
	ds_read_b128 v[146:149], v141 offset:8192
	ds_read_b128 v[152:155], v141 offset:12288
	v_exp_f32_e32 v138, v48
	v_exp_f32_e32 v142, v49
	s_waitcnt lgkmcnt(3)
	v_mfma_f32_32x32x16_bf16 v[16:31], v[128:131], v[80:83], v[16:31]
	v_exp_f32_e32 v151, v50
	v_add_f32_e32 v143, 0, v138
	v_add_f32_e32 v145, 0, v142
	v_exp_f32_e32 v156, v51
	ds_read_b128 v[48:51], v140 offset:8192
	ds_read_b128 v[128:131], v140 offset:12288
	v_exp_f32_e32 v52, v52
	s_waitcnt lgkmcnt(4)
	v_mfma_f32_32x32x16_bf16 v[0:15], v[134:137], v[80:83], v[0:15]
	v_exp_f32_e32 v53, v53
	v_exp_f32_e32 v54, v54
	v_exp_f32_e32 v55, v55
	v_add_f32_e32 v157, 0, v151
	v_add_f32_e32 v158, 0, v156
	v_add_f32_e32 v143, v52, v143
	s_waitcnt lgkmcnt(3)
	v_mfma_f32_32x32x16_bf16 v[16:31], v[146:149], v[84:87], v[16:31]
	v_add_f32_e32 v145, v53, v145
	v_add_f32_e32 v146, v54, v157
	ds_read_b128 v[80:83], v139 offset:8192
	ds_read_b128 v[134:137], v139 offset:12288
	v_exp_f32_e32 v56, v56
	v_exp_f32_e32 v57, v57
	v_exp_f32_e32 v58, v58
	s_waitcnt lgkmcnt(4)
	v_mfma_f32_32x32x16_bf16 v[0:15], v[152:155], v[84:87], v[0:15]
	v_add_f32_e32 v84, v55, v158
	v_exp_f32_e32 v59, v59
	v_exp_f32_e32 v60, v60
	v_exp_f32_e32 v32, v32
	v_exp_f32_e32 v33, v33
	v_exp_f32_e32 v34, v34
	s_waitcnt lgkmcnt(3)
	v_mfma_f32_32x32x16_bf16 v[16:31], v[48:51], v[88:91], v[16:31]
	v_cvt_pk_bf16_f32 v51, v54, v55
	v_exp_f32_e32 v54, v61
	v_exp_f32_e32 v55, v62
	v_exp_f32_e32 v61, v63
	v_exp_f32_e32 v35, v35
	v_add_f32_e32 v85, v56, v143
	v_add_f32_e32 v86, v57, v145
	v_add_f32_e32 v87, v58, v146
	v_add_f32_e32 v84, v59, v84
	v_cvt_pk_bf16_f32 v48, v138, v142
	v_cvt_pk_bf16_f32 v49, v151, v156
	v_cvt_pk_bf16_f32 v50, v52, v53
	v_add_f32_e32 v52, v60, v85
	v_add_f32_e32 v53, v54, v86
	v_add_f32_e32 v62, v55, v87
	v_add_f32_e32 v63, v61, v84
	v_exp_f32_e32 v36, v36
	v_exp_f32_e32 v37, v37
	v_exp_f32_e32 v38, v38
	v_exp_f32_e32 v39, v39
	s_waitcnt lgkmcnt(1)
	v_mfma_f32_32x32x16_bf16 v[16:31], v[80:83], v[92:95], v[16:31]
	v_add_f32_e32 v80, v32, v52
	v_add_f32_e32 v81, v33, v53
	v_cvt_pk_bf16_f32 v52, v56, v57
	v_cvt_pk_bf16_f32 v53, v58, v59
	v_cvt_pk_bf16_f32 v54, v60, v54
	v_cvt_pk_bf16_f32 v55, v55, v61
	v_add_f32_e32 v56, v34, v62
	v_add_f32_e32 v57, v35, v63
	v_exp_f32_e32 v40, v40
	v_add_f32_e32 v58, v36, v80
	v_add_f32_e32 v59, v37, v81
	v_add_f32_e32 v56, v38, v56
	v_exp_f32_e32 v41, v41
	v_add_f32_e32 v57, v39, v57
	v_mfma_f32_32x32x16_bf16 v[0:15], v[128:131], v[88:91], v[0:15]
	v_cvt_pk_bf16_f32 v32, v32, v33
	v_cvt_pk_bf16_f32 v33, v34, v35
	v_cvt_pk_bf16_f32 v34, v36, v37
	v_exp_f32_e32 v37, v42
	v_cvt_pk_bf16_f32 v35, v38, v39
	v_exp_f32_e32 v38, v43
	v_exp_f32_e32 v39, v44
	v_exp_f32_e32 v43, v45
	v_exp_f32_e32 v44, v46
	v_exp_f32_e32 v45, v47
	v_add_f32_e32 v58, v40, v58
	v_add_f32_e32 v59, v41, v59
	v_add_f32_e32 v36, v37, v56
	v_add_f32_e32 v42, v38, v57
	v_add_f32_e32 v56, v39, v58
	v_add_f32_e32 v58, v43, v59
	s_waitcnt lgkmcnt(0)
	v_mfma_f32_32x32x16_bf16 v[0:15], v[134:137], v[92:95], v[0:15]
	v_add_f32_e32 v57, v44, v36
	v_add_f32_e32 v59, v45, v42
	v_cvt_pk_bf16_f32 v36, v40, v41
	v_cvt_pk_bf16_f32 v37, v37, v38
	v_cvt_pk_bf16_f32 v38, v39, v43
	v_cvt_pk_bf16_f32 v39, v44, v45
	s_waitcnt lgkmcnt(0)
	s_barrier
	ds_read_b128 v[40:43], v144 offset:24576
	ds_read_b128 v[44:47], v144 offset:28672
	s_waitcnt lgkmcnt(1)
	v_mfma_f32_32x32x16_bf16 v[16:31], v[40:43], v[48:51], v[16:31]
	s_waitcnt lgkmcnt(0)
	v_mfma_f32_32x32x16_bf16 v[0:15], v[44:47], v[48:51], v[0:15]
	ds_read_b128 v[40:43], v141 offset:24576
	ds_read_b128 v[44:47], v141 offset:28672
	s_waitcnt lgkmcnt(1)
	v_mfma_f32_32x32x16_bf16 v[16:31], v[40:43], v[52:55], v[16:31]
	s_waitcnt lgkmcnt(0)
	v_mfma_f32_32x32x16_bf16 v[0:15], v[44:47], v[52:55], v[0:15]
	ds_read_b128 v[40:43], v140 offset:24576
	ds_read_b128 v[44:47], v140 offset:28672
	s_waitcnt lgkmcnt(1)
	v_mfma_f32_32x32x16_bf16 v[16:31], v[40:43], v[32:35], v[16:31]
	s_waitcnt lgkmcnt(0)
	v_mfma_f32_32x32x16_bf16 v[0:15], v[44:47], v[32:35], v[0:15]
	ds_read_b128 v[32:35], v139 offset:24576
	ds_read_b128 v[40:43], v139 offset:28672
	s_waitcnt lgkmcnt(1)
	v_mfma_f32_32x32x16_bf16 v[16:31], v[32:35], v[36:39], v[16:31]
	v_add_f32_e64 v32, v56, v58
	v_add_f32_e64 v33, v57, v59
	v_add_f32_e32 v32, v32, v33
	v_add_f32_e32 v32, v150, v32
	v_mov_b32_e32 v33, v32
	s_nop 1
	v_permlane32_swap_b32_e32 v32, v33
	v_add_f32_e32 v32, v32, v33
	v_div_scale_f32 v33, s[2:3], v32, v32, 1.0
	v_rcp_f32_e32 v34, v33
	s_waitcnt lgkmcnt(0)
	v_mfma_f32_32x32x16_bf16 v[0:15], v[40:43], v[36:39], v[0:15]
	s_waitcnt vmcnt(11)
	v_mov_b32_e32 v40, v127
	s_nop 1
	v_permlane32_swap_b32_e32 v125, v40
	v_fma_f32 v35, -v33, v34, 1.0
	v_fmac_f32_e32 v34, v35, v34
	v_div_scale_f32 v35, vcc, 1.0, v32, 1.0
	v_mul_f32_e32 v36, v35, v34
	v_fma_f32 v37, -v33, v36, v35
	v_fmac_f32_e32 v36, v37, v34
	v_fma_f32 v33, -v33, v36, v35
	v_div_fmas_f32 v33, v33, v34, v36
	v_mov_b32_e32 v35, v126
	v_div_fixup_f32 v34, v33, v32, 1.0
	s_nop 0
	v_permlane32_swap_b32_e32 v124, v35
	v_lshlrev_b32_e32 v38, 16, v124
	v_and_b32_e32 v39, 0xffff0000, v124
	v_mul_f32_e32 v16, v16, v34
	v_mul_f32_e32 v17, v17, v34
	v_mul_f32_e32 v18, v18, v34
	v_mul_f32_e32 v19, v19, v34
	v_mul_f32_e32 v16, v16, v38
	v_mul_f32_e32 v17, v17, v39
	v_lshlrev_b32_e32 v38, 16, v125
	v_and_b32_e32 v39, 0xffff0000, v125
	v_mul_f32_e32 v18, v18, v38
	v_mul_f32_e32 v19, v19, v39
	v_cvt_pk_bf16_f32 v16, v16, v17
	v_cvt_pk_bf16_f32 v17, v18, v19
	v_lshlrev_b32_e32 v18, 16, v35
	v_and_b32_e32 v19, 0xffff0000, v35
	v_mul_f32_e32 v20, v20, v34
	v_mul_f32_e32 v21, v21, v34
	v_mul_f32_e32 v22, v22, v34
	v_mul_f32_e32 v23, v23, v34
	v_mul_f32_e32 v18, v20, v18
	v_mul_f32_e32 v19, v21, v19
	v_lshlrev_b32_e32 v20, 16, v40
	v_and_b32_e32 v21, 0xffff0000, v40
	v_lshlrev_b64 v[32:33], 11, v[132:133]
	v_mul_f32_e32 v20, v22, v20
	v_mul_f32_e32 v21, v23, v21
	v_lshl_add_u64 v[32:33], s[6:7], 0, v[32:33]
	v_cvt_pk_bf16_f32 v18, v18, v19
	v_cvt_pk_bf16_f32 v19, v20, v21
	s_waitcnt vmcnt(10)
	v_mov_b32_e32 v22, v122
	v_lshl_add_u64 v[36:37], v[32:33], 0, v[176:177]
	v_permlane32_swap_b32_e32 v16, v18
	v_permlane32_swap_b32_e32 v17, v19
	v_permlane32_swap_b32_e32 v120, v22
	v_mov_b32_e32 v23, v123
	global_store_dwordx4 v[36:37], v[16:19], off offset:512
	s_nop 0
	v_permlane32_swap_b32_e32 v121, v23
	v_lshlrev_b32_e32 v16, 16, v120
	v_and_b32_e32 v17, 0xffff0000, v120
	v_mul_f32_e32 v18, v24, v34
	v_mul_f32_e32 v19, v25, v34
	v_mul_f32_e32 v20, v26, v34
	v_mul_f32_e32 v21, v27, v34
	v_mul_f32_e32 v16, v18, v16
	v_mul_f32_e32 v17, v19, v17
	v_lshlrev_b32_e32 v18, 16, v121
	v_and_b32_e32 v19, 0xffff0000, v121
	v_mul_f32_e32 v18, v20, v18
	v_mul_f32_e32 v19, v21, v19
	v_cvt_pk_bf16_f32 v16, v16, v17
	v_cvt_pk_bf16_f32 v17, v18, v19
	v_lshlrev_b32_e32 v18, 16, v22
	v_and_b32_e32 v19, 0xffff0000, v22
	v_mul_f32_e32 v20, v28, v34
	v_mul_f32_e32 v21, v29, v34
	v_mul_f32_e32 v0, v0, v34
	v_mul_f32_e32 v1, v1, v34
	v_mul_f32_e32 v18, v20, v18
	v_mul_f32_e32 v19, v21, v19
	v_lshlrev_b32_e32 v20, 16, v23
	v_and_b32_e32 v21, 0xffff0000, v23
	v_mul_f32_e32 v22, v30, v34
	v_mul_f32_e32 v23, v31, v34
	v_cvt_pk_bf16_f32 v18, v18, v19
	v_mul_f32_e32 v20, v22, v20
	v_mul_f32_e32 v21, v23, v21
	s_nop 0
	v_permlane32_swap_b32_e32 v16, v18
	v_cvt_pk_bf16_f32 v19, v20, v21
	s_nop 1
	v_permlane32_swap_b32_e32 v17, v19
	global_store_dwordx4 v[36:37], v[16:19], off offset:544
	v_mul_f32_e32 v2, v2, v34
	v_mul_f32_e32 v3, v3, v34
	v_mul_f32_e32 v4, v4, v34
	v_mul_f32_e32 v5, v5, v34
	s_waitcnt vmcnt(11)
	v_mov_b32_e32 v18, v118
	s_nop 1
	v_permlane32_swap_b32_e32 v116, v18
	v_mov_b32_e32 v19, v119
	s_nop 1
	v_permlane32_swap_b32_e32 v117, v19
	v_lshlrev_b32_e32 v16, 16, v116
	v_and_b32_e32 v17, 0xffff0000, v116
	v_mul_f32_e32 v0, v0, v16
	v_mul_f32_e32 v1, v1, v17
	v_lshlrev_b32_e32 v16, 16, v117
	v_and_b32_e32 v17, 0xffff0000, v117
	v_mul_f32_e32 v2, v2, v16
	v_mul_f32_e32 v3, v3, v17
	v_cvt_pk_bf16_f32 v0, v0, v1
	v_cvt_pk_bf16_f32 v1, v2, v3
	v_lshlrev_b32_e32 v2, 16, v18
	v_and_b32_e32 v3, 0xffff0000, v18
	v_mul_f32_e32 v2, v4, v2
	v_mul_f32_e32 v3, v5, v3
	v_lshlrev_b32_e32 v4, 16, v19
	v_and_b32_e32 v5, 0xffff0000, v19
	v_mul_f32_e32 v6, v6, v34
	v_mul_f32_e32 v7, v7, v34
	v_cvt_pk_bf16_f32 v2, v2, v3
	v_mul_f32_e32 v4, v6, v4
	v_mul_f32_e32 v5, v7, v5
	s_waitcnt vmcnt(10)
	v_mov_b32_e32 v6, v114
	v_cvt_pk_bf16_f32 v3, v4, v5
	v_permlane32_swap_b32_e32 v0, v2
	s_nop 0
	v_permlane32_swap_b32_e32 v1, v3
	v_permlane32_swap_b32_e32 v112, v6
	v_mov_b32_e32 v7, v115
	global_store_dwordx4 v[36:37], v[0:3], off offset:576
	s_nop 0
	v_permlane32_swap_b32_e32 v113, v7
	v_lshlrev_b32_e32 v0, 16, v112
	v_and_b32_e32 v1, 0xffff0000, v112
	v_mul_f32_e32 v2, v8, v34
	v_mul_f32_e32 v3, v9, v34
	v_mul_f32_e32 v4, v10, v34
	v_mul_f32_e32 v5, v11, v34
	v_mul_f32_e32 v0, v2, v0
	v_mul_f32_e32 v1, v3, v1
	v_lshlrev_b32_e32 v2, 16, v113
	v_and_b32_e32 v3, 0xffff0000, v113
	v_mul_f32_e32 v2, v4, v2
	v_mul_f32_e32 v3, v5, v3
	v_cvt_pk_bf16_f32 v0, v0, v1
	v_cvt_pk_bf16_f32 v1, v2, v3
	v_lshlrev_b32_e32 v2, 16, v6
	v_and_b32_e32 v3, 0xffff0000, v6
	v_mul_f32_e32 v4, v12, v34
	v_mul_f32_e32 v5, v13, v34
	s_mov_b64 s[2:3], 0x200
	v_mul_f32_e32 v2, v4, v2
	v_mul_f32_e32 v3, v5, v3
	v_lshlrev_b32_e32 v4, 16, v7
	v_and_b32_e32 v5, 0xffff0000, v7
	v_mul_f32_e32 v6, v14, v34
	v_mul_f32_e32 v7, v15, v34
	v_cvt_pk_bf16_f32 v2, v2, v3
	v_mul_f32_e32 v4, v6, v4
	v_mul_f32_e32 v5, v7, v5
	v_lshl_add_u64 v[32:33], v[36:37], 0, s[2:3]
	v_cvt_pk_bf16_f32 v3, v4, v5
	v_permlane32_swap_b32_e32 v0, v2
	s_nop 0
	v_permlane32_swap_b32_e32 v1, v3
	s_branch .LBB0_876
